# DP deferred prep: phase 0 transposes only layer-0 w_in/w_br/w_out + folds/mod/rope; remaining weight transposes run on workgroups idle at the end of L0 sub1 / L0 sub4 / L1 sub1
# speedup vs baseline: 1.0814x; 1.0207x over previous
; __device__ void phase_prep(const Params& p, LAS unsigned char* lds) {
;     ...
;     constexpr int I_TR = 2 * T_L, I_POOL = I_TR + 128, I_FOUR = I_POOL + 256, I_MOD = I_FOUR + 192, I_ALL = I_MOD + 1;
;     for (int prep_rep = 0; prep_rep < ((PROBE >= 301 && PROBE <= 304) ? 2 : 1); ++prep_rep)
;     for (int it = blockIdx.x; it < I_ALL; it += gridDim.x) {
;     ...
;         if (prep_rep == 1) { const int cls = (it < I_TR) ? 301 : (it < I_FOUR) ? 302 : (it < I_MOD) ? 303 : 304; if (cls != PROBE) continue; }
;     ...
;         if (it < I_TR) {
.LBB0_14:
	s_andn2_b64 vcc, exec, s[0:1]
	s_cbranch_vccnz .LBB0_735
	s_mov_b32 s0, 0
	v_writelane_b32 v252, s0, 0
	v_writelane_b32 v252, s26, 1
	s_movk_i32 s0, 0x100
	v_writelane_b32 v252, s0, 2
	s_movk_i32 s0, 0x3b1
	v_writelane_b32 v252, s0, 3
	s_movk_i32 s0, 0x170
	v_writelane_b32 v252, s0, 5
	s_branch .LBB0_650

; #define LAS __attribute__((address_space(3)))
; __device__ __forceinline__ int otid() { int t = threadIdx.x; asm volatile("" : "+v"(t)); return t; }
; #define GAS __attribute__((address_space(1)))
; __device__ __forceinline__ void fixup_tile(const bf16_t* HBp, bf16_t* ACTp, const float* cwp, int pm) {
;     const int tid = otid();
;     if (pm >= 64 || tid >= 352) return;
;     GAS const bf16_t* HB = (GAS const bf16_t*)(unsigned long long)HBp;
;     GAS bf16_t* ACT = (GAS bf16_t*)(unsigned long long)ACTp;
;     GAS const float* cw = (GAS const float*)(unsigned long long)cwp;
;     const int ch = tid * 8, col = 256 * (ch >> 7) + (ch & 127);
;     const bool up_nb = (pm & 15) != 0, dn_nb = (pm & 15) != 15;
;     const u32x4 z = {0u, 0u, 0u, 0u};
;     GAS const bf16_t* h0 = HB + (size_t)pm * 4 * 5632 + col;
; __device__ __forceinline__ bool gemm_phase(LAS unsigned char* lds, int l, int sub, int gi, bool dry = false) {
;     ...
;     if (sub == 8) {
;         LAS const Params* lp = (LAS const Params*)(lds + PRM_OFF);
;         unsigned char* ws = lp->ws; const float* cwp = lp->conv_w + (size_t)l * 3 * 5632;
;         Unit fu;
;         for (int i = 0; unit_next(g, i, fu); ++i) fixup_tile((const bf16_t*)(ws + OFF_HB), (bf16_t*)(ws + OFF_ACT), cwp, fu.pm);
.LBB0_243:
	s_cmp_lg_u32 s59, 0
	s_cbranch_scc1 .Lmy_nodelay
	v_readlane_b32 s4, v255, 0
	s_nop 3
	s_cmp_lg_u32 s17, 6
	s_cbranch_scc1 .Lmy_dl0
	s_cmp_lg_u32 s4, 1
	s_cbranch_scc1 .Lmy_dl0
	s_cmp_lt_u32 s26, 128
	s_cbranch_scc1 .Lmy_nodelay
	s_sleep 127
	s_sleep 127
	s_sleep 127
	s_sleep 127
	s_branch .Lmy_nodelay
.Lmy_dl0:
.Lmy_nodelay:
	v_cndmask_b32_e64 v0, 0, 1, s[22:23]
	v_readfirstlane_b32 s57, v3
	v_readfirstlane_b32 s4, v0
	s_bitcmp1_b32 s4, 0
	v_readfirstlane_b32 s56, v2
	v_readfirstlane_b32 s1, v4
	s_cselect_b64 s[18:19], -1, 0
	s_cmp_lt_i32 s17, 8
	s_mov_b64 s[4:5], -1
	s_cbranch_scc1 .LBB0_280
	s_cmp_eq_u32 s17, 8
	s_cbranch_scc0 .LBB0_279
	v_readlane_b32 s4, v254, 35
	v_readlane_b32 s6, v255, 10
	v_readlane_b32 s7, v255, 11
	v_mov_b32_e32 v0, s4
	ds_read_b64 v[0:1], v0
	s_mov_b64 s[42:43], s[26:27]
	s_waitcnt lgkmcnt(0)
	v_readfirstlane_b32 s4, v0
	v_readfirstlane_b32 s5, v1
	s_add_u32 s20, s4, s6
	s_addc_u32 s21, s5, s7
	s_cmp_lg_u32 s1, 0
	s_cselect_b64 s[22:23], -1, 0
	s_ashr_i32 s63, s62, 31
	s_add_i32 s6, s62, s11
	s_lshl_b64 s[24:25], s[62:63], 6
	s_lshl_b32 s10, s6, 2
	s_lshl_b32 s12, s62, 2
	s_add_u32 s28, s20, 0x2c00
	s_addc_u32 s29, s21, 0
	s_add_u32 s34, s20, 0x5800
	s_addc_u32 s35, s21, 0
	s_add_u32 s36, s20, 0x8400
	s_addc_u32 s37, s21, 0
	s_add_u32 s38, s20, 0xb000
	s_addc_u32 s39, s21, 0
	s_add_u32 s40, s20, 0xdc00
	s_addc_u32 s41, s21, 0
	s_abs_i32 s15, s6
	v_cvt_f32_u32_e32 v0, s15
	s_mov_b64 s[4:5], 0xc100000
	s_abs_i32 s48, s12
	v_lshl_add_u64 v[102:103], v[98:99], 0, s[4:5]
	v_rcp_iflag_f32_e32 v0, v0
	s_sub_i32 s4, 0, s15
	s_movk_i32 s63, 0xff00
	s_ashr_i32 s13, s6, 31
	v_mul_f32_e32 v0, 0x4f7ffffe, v0
	v_cvt_u32_f32_e32 v0, v0
	s_bfe_i32 s33, s62, 0x1001d
	v_readfirstlane_b32 s5, v0
	v_cvt_f32_u32_e32 v0, s48
	s_mul_i32 s4, s4, s5
	s_mul_hi_u32 s4, s5, s4
	s_add_i32 s31, s5, s4
	v_rcp_iflag_f32_e32 v0, v0
	s_sub_i32 s4, 0, s48
	v_mul_f32_e32 v0, 0x4f7ffffe, v0
	v_cvt_u32_f32_e32 v0, v0
	s_nop 0
	v_readfirstlane_b32 s5, v0
	s_mul_i32 s4, s4, s5
	s_mul_hi_u32 s4, s5, s4
	s_add_i32 s49, s5, s4
	s_lshl_b32 s4, s62, 6
	s_sub_i32 s50, 0, s4
	s_branch .LBB0_248

; __device__ void phase_prep(const Params& p, LAS unsigned char* lds) {
;     ...
;         } else {
;             float* rope = (float*)(p.ws + OFF_ROPE); float* tw = (float*)(p.ws + OFF_TW);
;             for (int i = tid; i < 1024; i += 512) { const int pos = i >> 4, f = i & 15; const float inv = powf(10000.f, -(float)f / 16.f); const float ang = (float)pos * inv;
;                 rope[2 * i] = cosf(ang); rope[2 * i + 1] = sinf(ang); }
;             for (int i = tid; i < 4095; i += 512) { const int sh = 31 - __clz(i + 1), half = 1 << sh, j = i + 1 - half; float sv, cv; sincospif((float)j / (float)half, &sv, &cv); tw[2 * i] = cv; tw[2 * i + 1] = sv; }
; __global__ void __launch_bounds__(512) mega(Params pk) {
;     ...
;         for (int rep = 0; rep < nrep; ++rep) {
;             const bool dry = (PROBE >= 200) && (rep == 0) && (nrep == 2);
;             if (ph == 0) { const Params p = load_params(lp); phase_prep(p, lds); }
;             else if (ph == N_PHASES - 1) { const Params p = load_params(lp); phase_final(p); }
;             else if (sub == 0 || sub == 5) { const Params p = load_params(lp); phase_norm(p, l, sub == 5); }
;             else if (sub == 2) { const Params p = load_params(lp); phase_mix(p, l, lds); }
;             else { for (int gi = 0; gi < 6; ++gi) { if (!gemm_phase(lds, l, sub, gi, dry)) break; } }
;             if (rep + 1 < nrep) xcd_barrier(xb);
;         }
;         if (ph + 1 < ph_hi) xcd_barrier(xb);
.LBB0_649:
	s_cmp_eq_u32 s16, 2
	s_cbranch_scc1 .Lmy_dp_m0
	s_cmp_eq_u32 s16, 5
	s_cbranch_scc1 .Lmy_dp_m1
	s_cmp_eq_u32 s16, 10
	s_cbranch_scc1 .Lmy_dp_m2
	s_branch .LBB0_735
.Lmy_dp_m0:
	s_cmp_lt_u32 s26, 132
	s_cbranch_scc1 .LBB0_735
	s_sub_i32 s0, s26, 132
	s_movk_i32 s1, 124
	s_movk_i32 s88, 352
	s_movk_i32 s89, 368
	s_branch .Lmy_dp_go
.Lmy_dp_m1:
	s_cmp_lt_u32 s26, 16
	s_cbranch_scc1 .LBB0_735
	s_sub_i32 s0, s26, 16
	s_movk_i32 s1, 240
	s_movk_i32 s88, 544
	s_movk_i32 s89, 720
	s_branch .Lmy_dp_go
.Lmy_dp_m2:
	s_cmp_lt_u32 s26, 84
	s_cbranch_scc1 .LBB0_735
	s_sub_i32 s0, s26, 84
	s_movk_i32 s1, 172
	s_movk_i32 s88, 528
	s_movk_i32 s89, 1264
	s_branch .Lmy_dp_go
.Lmy_dp_go:
	v_writelane_b32 v252, s89, 0
	v_writelane_b32 v252, s0, 1
	v_writelane_b32 v252, s1, 2
	v_writelane_b32 v252, s88, 3
	s_movk_i32 s0, 0x7fff
	v_writelane_b32 v252, s0, 5
.LBB0_650:
	v_readlane_b32 s0, v254, 42
	v_mov_b32_e32 v26, v210
	s_waitcnt lgkmcnt(0)
	v_mov_b32_e32 v0, s0
	v_readlane_b32 s0, v254, 43
	s_nop 1
	v_mov_b32_e32 v1, s0
	v_readlane_b32 s0, v254, 44
	ds_read_b64 v[44:45], v0
	ds_read2_b64 v[0:3], v1 offset1:1
	v_mov_b32_e32 v4, s0
	v_readlane_b32 s0, v254, 45
	s_nop 1
	v_mov_b32_e32 v5, s0
	v_readlane_b32 s0, v254, 46
	ds_read_b64 v[16:17], v4
	ds_read_b64 v[18:19], v5
	v_mov_b32_e32 v4, s0
	v_readlane_b32 s0, v254, 47
	s_nop 1
	v_mov_b32_e32 v8, s0
	v_readlane_b32 s0, v254, 48
	ds_read_b128 v[4:7], v4
	ds_read_b128 v[8:11], v8
	v_mov_b32_e32 v12, s0
	v_readlane_b32 s0, v254, 49
	s_nop 1
	v_mov_b32_e32 v20, s0
	v_readlane_b32 s0, v254, 50
	ds_read_b128 v[12:15], v12
	ds_read_b64 v[20:21], v20
	v_mov_b32_e32 v22, s0
	v_readlane_b32 s0, v254, 25
	s_nop 1
	v_mov_b32_e32 v24, s0
	ds_read_b64 v[22:23], v22
	ds_read_b64 v[24:25], v24
	v_readlane_b32 s0, v253, 13
	v_readlane_b32 s1, v253, 14
	s_andn2_b64 vcc, exec, s[0:1]
	s_cbranch_vccnz .LBB0_735
	v_cvt_f32_i32_e32 v27, v26
	s_movk_i32 s0, 0x1400
	v_and_b32_e32 v28, 63, v26
	v_ashrrev_i32_e32 v29, 6, v26
	v_cmp_gt_i32_e64 s[40:41], s0, v26
	v_lshlrev_b32_e32 v51, 7, v29
	v_lshl_add_u32 v50, v28, 2, 0
	s_movk_i32 s0, 0x500
	v_mad_u64_u32 v[30:31], s[0:1], v29, s0, v[50:51]
	v_mul_f32_e32 v27, 0x3d000000, v27
	s_movk_i32 s0, 0x140
	v_mul_f32_e64 v32, |v27|, 0.5
	v_cmp_gt_i32_e64 s[42:43], s0, v26
	s_movk_i32 s0, 0x400
	v_fract_f32_e32 v33, v32
	v_cmp_gt_i32_e64 s[44:45], s0, v26
	s_movk_i32 s0, 0xfff
	v_add_f32_e32 v33, v33, v33
	v_cmp_neq_f32_e32 vcc, s59, v32
	v_cmp_gt_i32_e64 s[46:47], s0, v26
	v_cmp_gt_f32_e64 s[0:1], |v27|, 1.0
	v_cndmask_b32_e32 v32, 0, v33, vcc
	v_and_b32_e32 v31, 0x7fffffff, v27
	v_cndmask_b32_e64 v32, |v27|, v32, s[0:1]
	v_add_f32_e32 v33, v32, v32
	v_rndne_f32_e32 v33, v33
	v_fmac_f32_e32 v32, -0.5, v33
	v_mul_f32_e32 v34, v32, v32
	v_fmamk_f32 v35, v34, 0x3e75aa41, v246
	v_fmaak_f32 v35, v34, v35, 0x40234736
	v_fmaak_f32 v35, v34, v35, 0xc0a55e0e
	v_mul_f32_e32 v36, v32, v34
	v_mul_f32_e32 v35, v36, v35
	v_cvt_i32_f32_e32 v33, v33
	v_fmac_f32_e32 v35, 0x40490fdb, v32
	v_fmamk_f32 v32, v34, 0x3d4be544, v234
	v_fmaak_f32 v32, v34, v32, 0xbfaad1da
	v_fmaak_f32 v32, v34, v32, 0x4081e0d3
	v_fmaak_f32 v32, v34, v32, 0xc09de9e6
	v_fma_f32 v32, v34, v32, 1.0
	v_lshlrev_b32_e32 v34, 30, v33
	v_and_b32_e32 v33, 1, v33
	v_cmp_eq_u32_e32 vcc, 0, v33
	v_xor_b32_e32 v31, v31, v27
	v_and_b32_e32 v36, 0x80000000, v34
	v_cndmask_b32_e32 v33, v32, v35, vcc
	v_xor_b32_e32 v31, v31, v33
	v_xor_b32_e32 v33, v31, v36
	v_xor_b32_e32 v31, 0x80000000, v35
	v_cndmask_b32_e32 v31, v31, v32, vcc
	v_cmp_class_f32_e64 vcc, v27, s54
	v_ashrrev_i32_e32 v27, 3, v26
	v_mul_lo_u32 v36, v29, 24
	v_bitop3_b32 v31, v31, v34, s33 bitop3:0x78
	v_and_b32_e32 v34, -8, v27
	v_and_b32_e32 v27, 15, v26
	v_and_b32_e32 v56, 56, v36
	v_mul_lo_u32 v36, v29, 40
	v_and_b32_e32 v57, 56, v36
	v_mul_lo_u32 v36, v29, 48
	v_cvt_f32_ubyte0_e32 v27, v27
	v_and_b32_e32 v58, 48, v36
	v_mul_lo_u32 v36, v29, 56
	v_mul_f32_e32 v27, 0xbd800000, v27
	v_cndmask_b32_e32 v31, v237, v31, vcc
	v_cndmask_b32_e32 v65, v237, v33, vcc
	v_and_b32_e32 v59, 56, v36
	v_cmp_eq_f32_e32 vcc, 0, v27
	v_mov_b32_e32 v36, 0x461c4000
	s_mov_b32 s0, 0x3f2aaaab
	v_cndmask_b32_e64 v52, v36, 1.0, vcc
	v_frexp_mant_f32_e32 v36, v52
	v_cmp_gt_f32_e64 s[50:51], s0, v36
	s_mov_b32 s0, 0x3f317218
	s_movk_i32 s2, 0x204
	v_cndmask_b32_e64 v37, 1.0, 2.0, s[50:51]
	v_mul_f32_e32 v36, v36, v37
	v_add_f32_e32 v39, 1.0, v36
	v_rcp_f32_e32 v46, v39
	v_add_f32_e32 v37, -1.0, v39
	v_sub_f32_e32 v41, v36, v37
	v_add_f32_e32 v37, -1.0, v36
	v_mul_f32_e32 v47, v37, v46
	v_mul_f32_e32 v38, v39, v47
	v_fma_f32 v40, v47, v39, -v38
	v_fmac_f32_e32 v40, v47, v41
	v_add_f32_e32 v36, v38, v40
	v_sub_f32_e32 v39, v37, v36
	v_pk_add_f32 v[42:43], v[36:37], v[38:39] neg_lo:[0,1] neg_hi:[0,1]
	v_mov_b32_e32 v41, v36
	v_pk_add_f32 v[36:37], v[42:43], v[40:41] neg_lo:[0,1] neg_hi:[0,1]
	v_mov_b32_e32 v40, 0x3e91f4c4
	v_add_f32_e32 v36, v36, v37
	v_add_f32_e32 v36, v39, v36
	v_mul_f32_e32 v37, v46, v36
	v_add_f32_e32 v36, v47, v37
	v_sub_f32_e32 v38, v36, v47
	v_sub_f32_e32 v53, v37, v38
	v_mul_f32_e32 v37, v36, v36
	v_fma_f32 v39, v36, v36, -v37
	v_add_f32_e32 v38, v53, v53
	v_fmac_f32_e32 v39, v36, v38
	v_add_f32_e32 v38, v37, v39
	v_fmamk_f32 v40, v38, 0x3e76c4e1, v40
	v_fmaak_f32 v40, v38, v40, 0x3ecccdef
	v_sub_f32_e32 v37, v38, v37
	v_sub_f32_e32 v54, v39, v37
	v_mul_f32_e32 v37, v38, v40
	v_fma_f32 v39, v38, v40, -v37
	v_fmac_f32_e32 v39, v54, v40
	v_add_f32_e32 v40, v37, v39
	v_add_f32_e32 v41, 0x3f2aaaaa, v40
	v_sub_f32_e32 v37, v40, v37
	v_sub_f32_e32 v37, v39, v37
	v_add_f32_e32 v39, 0xbf2aaaaa, v41
	v_add_f32_e32 v37, 0x31739010, v37
	v_sub_f32_e32 v39, v40, v39
; __device__ void phase_prep(const Params& p, LAS unsigned char* lds) {
;     ...
;     constexpr int I_TR = 2 * T_L, I_POOL = I_TR + 128, I_FOUR = I_POOL + 256, I_MOD = I_FOUR + 192, I_ALL = I_MOD + 1;
;     for (int prep_rep = 0; prep_rep < ((PROBE >= 301 && PROBE <= 304) ? 2 : 1); ++prep_rep)
;     for (int it = blockIdx.x; it < I_ALL; it += gridDim.x) {
;     ...
;         if (prep_rep == 1) { const int cls = (it < I_TR) ? 301 : (it < I_FOUR) ? 302 : (it < I_MOD) ? 303 : 304; if (cls != PROBE) continue; }
;     ...
;         if (it < I_TR) {
;             const int l = it / T_L; int j = it % T_L;
;             unsigned char* wb = p.ws + OFF_W + (size_t)l * LW;
;     ...
;         } else {
;             float* rope = (float*)(p.ws + OFF_ROPE); float* tw = (float*)(p.ws + OFF_TW);
;             for (int i = tid; i < 1024; i += 512) { const int pos = i >> 4, f = i & 15; const float inv = powf(10000.f, -(float)f / 16.f); const float ang = (float)pos * inv;
;                 rope[2 * i] = cosf(ang); rope[2 * i + 1] = sinf(ang); }
;             for (int i = tid; i < 4095; i += 512) { const int sh = 31 - __clz(i + 1), half = 1 << sh, j = i + 1 - half; float sv, cv; sincospif((float)j / (float)half, &sv, &cv); tw[2 * i] = cv; tw[2 * i + 1] = sv; }
	v_pk_mul_f32 v[42:43], v[36:37], v[38:39]
	v_pk_add_f32 v[46:47], v[36:37], v[38:39]
	v_fma_f32 v40, v38, v36, -v42
	v_fmac_f32_e32 v40, v38, v53
	v_mov_b32_e32 v43, v47
	v_fmac_f32_e32 v40, v54, v36
	v_pk_add_f32 v[38:39], v[42:43], v[40:41]
	v_ldexp_f32 v54, v53, 1
	v_sub_f32_e32 v37, v38, v42
	v_sub_f32_e32 v37, v40, v37
	v_sub_f32_e32 v40, v41, v39
	v_add_f32_e32 v46, v47, v40
	v_pk_mul_f32 v[40:41], v[38:39], v[38:39] op_sel:[0,1] op_sel_hi:[1,0]
	v_cvt_f64_f32_e32 v[42:43], v52
	v_frexp_exp_i32_f64_e32 v41, v[42:43]
	v_subbrev_co_u32_e64 v41, s[50:51], 0, v41, s[50:51]
	v_cvt_f32_i32_e32 v41, v41
	v_fma_f32 v42, v38, v39, -v40
	v_fmac_f32_e32 v42, v38, v46
	v_fmac_f32_e32 v42, v37, v39
	v_mul_f32_e32 v38, 0x3f317218, v41
	v_fma_f32 v46, v41, s0, -v38
	v_fmac_f32_e32 v46, 0xb102e308, v41
	v_ldexp_f32 v47, v36, 1
	v_add_f32_e32 v39, v40, v42
	v_pk_add_f32 v[36:37], v[38:39], v[46:47]
	v_mov_b32_e32 v52, v39
	v_mov_b32_e32 v53, v37
	v_mov_b32_e32 v41, v47
	v_pk_add_f32 v[40:41], v[52:53], v[40:41] neg_lo:[0,1] neg_hi:[0,1]
	v_mov_b32_e32 v43, v39
	v_pk_add_f32 v[40:41], v[42:43], v[40:41] neg_lo:[0,1] neg_hi:[0,1]
	v_mov_b32_e32 v47, v36
	v_add_f32_e32 v39, v54, v40
	v_add_f32_e32 v39, v39, v41
	v_pk_add_f32 v[40:41], v[36:37], v[38:39] neg_lo:[0,1] neg_hi:[0,1]
	v_pk_add_f32 v[42:43], v[36:37], v[38:39]
	v_mov_b32_e32 v38, v39
	v_mov_b32_e32 v41, v43
	v_pk_add_f32 v[52:53], v[46:47], v[40:41] neg_lo:[0,1] neg_hi:[0,1]
	v_pk_add_f32 v[40:41], v[46:47], v[40:41]
	v_mov_b32_e32 v39, v36
	v_pk_add_f32 v[46:47], v[40:41], v[36:37] op_sel:[1,0] op_sel_hi:[0,1] neg_lo:[0,1] neg_hi:[0,1]
	v_pk_add_f32 v[54:55], v[42:43], v[46:47] op_sel_hi:[1,0] neg_lo:[0,1] neg_hi:[0,1]
	v_mov_b32_e32 v42, v43
	v_mov_b32_e32 v43, v41
	v_pk_mov_b32 v[46:47], v[36:37], v[46:47] op_sel:[1,0]
	v_mov_b32_e32 v54, v52
	v_pk_add_f32 v[42:43], v[42:43], v[46:47] neg_lo:[0,1] neg_hi:[0,1]
	v_mov_b32_e32 v53, v41
	v_pk_add_f32 v[36:37], v[38:39], v[42:43] neg_lo:[0,1] neg_hi:[0,1]
	s_mov_b32 s1, 0x42b17218
	v_pk_add_f32 v[38:39], v[54:55], v[36:37]
	s_mov_b32 s0, 0xc2ce8ed0
	v_pk_add_f32 v[42:43], v[38:39], v[38:39] op_sel:[0,1] op_sel_hi:[1,0]
	v_lshlrev_b32_e32 v48, 6, v34
	v_pk_add_f32 v[40:41], v[40:41], v[42:43] op_sel:[1,0] op_sel_hi:[0,1]
	v_mov_b32_e32 v39, v40
	v_pk_add_f32 v[46:47], v[38:39], v[52:53] neg_lo:[0,1] neg_hi:[0,1]
	v_mov_b32_e32 v37, v42
	v_sub_f32_e32 v38, v38, v46
	v_pk_add_f32 v[36:37], v[36:37], v[46:47] neg_lo:[0,1] neg_hi:[0,1]
	v_sub_f32_e32 v38, v52, v38
	v_add_f32_e32 v36, v36, v38
	v_add_f32_e32 v36, v36, v37
	v_add_f32_e32 v37, v40, v36
	v_sub_f32_e32 v38, v37, v40
	v_sub_f32_e32 v36, v36, v38
	v_mul_f32_e32 v38, v27, v37
	v_fma_f32 v37, v27, v37, -v38
	v_fmac_f32_e32 v37, v27, v36
	v_add_f32_e32 v36, v38, v37
	v_cmp_class_f32_e64 s[50:51], v38, s2
	v_sub_f32_e32 v39, v36, v38
	v_sub_f32_e32 v37, v37, v39
	v_cndmask_b32_e64 v36, v36, v38, s[50:51]
	v_cmp_eq_f32_e64 s[50:51], s1, v36
	v_mov_b32_e32 v38, 0x37000000
	v_lshlrev_b32_e32 v32, 3, v29
	v_cndmask_b32_e64 v38, 0, v38, s[50:51]
	v_sub_f32_e32 v39, v36, v38
	v_mul_f32_e32 v40, 0x3fb8aa3b, v39
	v_fma_f32 v41, v39, s30, -v40
	v_rndne_f32_e32 v42, v40
	v_fmac_f32_e32 v41, 0x32a5705f, v39
	v_sub_f32_e32 v40, v40, v42
	v_add_f32_e32 v40, v40, v41
	v_exp_f32_e32 v40, v40
	v_cvt_i32_f32_e32 v41, v42
	v_cmp_neq_f32_e64 s[50:51], |v36|, s59
	v_lshlrev_b32_e32 v42, 1, v26
	v_ashrrev_i32_e32 v43, 31, v42
	v_cndmask_b32_e64 v36, 0, v37, s[50:51]
	v_ldexp_f32 v37, v40, v41
	v_cmp_ngt_f32_e64 s[50:51], s0, v39
	v_add_f32_e32 v36, v38, v36
	v_mov_b32_e32 v38, 0x7f800000
	v_cndmask_b32_e64 v37, 0, v37, s[50:51]
	v_cmp_nlt_f32_e64 s[50:51], s1, v39
	v_cmp_neq_f32_e64 s[0:1], v27, |v27|
	s_waitcnt lgkmcnt(0)
	v_lshl_add_u64 v[46:47], v[42:43], 2, v[24:25]
	v_cndmask_b32_e64 v37, v38, v37, s[50:51]
	v_fma_f32 v36, v37, v36, v37
	v_cmp_class_f32_e64 s[50:51], v37, s2
	v_ashrrev_i32_e32 v49, 31, v48
	v_lshlrev_b32_e32 v60, 8, v29
	v_cndmask_b32_e64 v36, v36, v37, s[50:51]
	v_cndmask_b32_e64 v37, v38, 0, s[0:1]
	v_cmp_class_f32_e64 s[0:1], v27, s2
	v_lshlrev_b32_e32 v27, 5, v29
	v_and_b32_e32 v27, 0xe0, v27
	v_cndmask_b32_e64 v37, v37, 1.0, vcc
	v_add_u32_e32 v108, 0, v27
	v_and_b32_e32 v27, 0xc0, v26
	v_cndmask_b32_e64 v73, |v36|, v37, s[0:1]
	v_add_u32_e32 v109, 0, v27
	v_and_b32_e32 v27, 0x80, v51
	s_mov_b64 s[0:1], 0x40000
	v_add_u32_e32 v110, 0, v27
	v_lshl_add_u64 v[36:37], v[24:25], 0, s[0:1]
	s_mov_b64 s[0:1], 0x44000
	v_max_i32_e32 v27, 0xdff, v26
	v_lshl_add_u64 v[38:39], v[24:25], 0, s[0:1]
	s_mov_b64 s[0:1], 0x600000
	v_sub_u32_e32 v27, v27, v26
	v_lshl_add_u64 v[40:41], v[24:25], 0, s[0:1]
	v_add_u32_e32 v27, 0x1ff, v27
	s_mov_b64 s[0:1], 0x44004
	v_lshrrev_b32_e32 v96, 9, v27
	v_lshl_add_u64 v[46:47], v[46:47], 0, s[0:1]
	s_movk_i32 s0, 0x5ff
	v_cmp_lt_u32_e32 vcc, s0, v27
	v_cmp_gt_i32_e64 s[50:51], 0, v27
	v_lshl_add_u32 v27, v96, 10, v42
	v_lshlrev_b64 v[52:53], 12, v[96:97]
	v_cmp_lt_i32_e64 s[52:53], v27, v42
	v_lshl_add_u64 v[52:53], v[46:47], 0, v[52:53]
	s_or_b64 s[0:1], s[52:53], s[50:51]
	v_cmp_lt_u64_e64 s[50:51], v[52:53], v[46:47]
	s_or_b64 s[0:1], s[0:1], s[50:51]
	s_xor_b64 s[0:1], s[0:1], -1
	v_add_u32_e32 v54, 1, v96
	s_and_b64 s[60:61], vcc, s[0:1]
	v_mad_i64_i32 v[2:3], s[0:1], v51, s28, v[2:3]
	v_and_b32_e32 v43, 0xfffffe, v54
	v_ashrrev_i32_e32 v47, 31, v26
	v_mov_b32_e32 v46, v26
	s_mov_b64 s[0:1], 0xba000
	v_cmp_gt_i32_e64 s[48:49], 64, v26
	v_lshl_add_u32 v69, v26, 2, 0
	v_ashrrev_i32_e32 v33, 31, v32
	v_ashrrev_i32_e32 v35, 31, v34
	v_or_b32_e32 v71, 0x60, v51
	v_lshl_add_u32 v75, v59, 2, 0
	v_or_b32_e32 v77, 1, v32
	v_lshl_add_u32 v111, v56, 2, 0
	v_lshl_add_u32 v112, v57, 2, 0
	v_lshl_add_u32 v113, v58, 2, 0
	v_lshl_add_u32 v114, v43, 9, v26
	v_add_u32_e32 v27, 0x200, v26
	v_cmp_ne_u32_e64 s[50:51], v54, v43
	v_lshl_add_u64 v[44:45], v[46:47], 2, v[44:45]
	v_subrev_u32_e32 v115, 32, v51
	v_lshl_add_u32 v116, v29, 9, 0
	v_lshl_add_u64 v[46:47], v[2:3], 0, s[0:1]
	v_lshl_add_u64 v[48:49], v[48:49], 2, v[4:5]
	v_add_u32_e32 v117, v50, v60
	v_readlane_b32 s8, v254, 23
	s_nop 3
	s_sub_i32 s8, s8, s26
	v_writelane_b32 v252, s8, 4
	s_branch .Lmy_dp_first
.LBB0_652:
	v_readlane_b32 s88, v252, 1
	v_readlane_b32 s89, v252, 2
	s_nop 3
	s_add_i32 s88, s88, s89
	v_writelane_b32 v252, s88, 1
	s_nop 1
.Lmy_dp_first:
	v_readlane_b32 s88, v252, 1
	v_readlane_b32 s89, v252, 3
	s_nop 3
	s_cmp_ge_i32 s88, s89
	s_cbranch_scc1 .LBB0_734
	v_readlane_b32 s17, v252, 0
	v_readlane_b32 s89, v252, 5
	s_nop 3
	s_add_i32 s17, s17, s88
	s_cmp_lt_i32 s17, s89
	s_cbranch_scc1 .Lmy_dp_it
	s_addk_i32 s17, 0x590
.Lmy_dp_it:
	v_readlane_b32 s8, v252, 4
	s_nop 3
	s_add_i32 s8, s8, s17
